# weight-conversion loops: next-to-current register rotation and its wait moved to just before the following tile loads are issued
# speedup vs baseline: 1.0059x; 1.0015x over previous
.Lgkp_0:
	s_waitcnt vmcnt(0)
	v_mov_b64_e32 v[6:7], v[18:19]
	v_mov_b64_e32 v[10:11], v[14:15]
	v_mov_b64_e32 v[4:5], v[16:17]
	v_mov_b64_e32 v[8:9], v[12:13]
	s_branch .LBB0_338
.Lcvr_LBB0_338:
	s_waitcnt vmcnt(1)
	v_mov_b64_e32 v[18:19], v[6:7]
	v_mov_b64_e32 v[14:15], v[10:11]
	v_mov_b64_e32 v[16:17], v[4:5]
	v_mov_b64_e32 v[12:13], v[8:9]
	s_branch .LBB0_349

.LBB0_337:
	v_mad_i64_i32 v[2:3], s[22:23], v2, s33, 0
	v_lshl_add_u64 v[2:3], v[2:3], 1, s[0:1]
	s_ashr_i32 s43, s42, 31
	v_lshl_add_u64 v[2:3], s[42:43], 1, v[2:3]
	v_lshlrev_b32_e32 v0, 1, v20
	v_lshl_add_u64 v[2:3], v[2:3], 0, v[0:1]
	global_store_dwordx4 v[2:3], v[12:15], off sc1
	s_add_i32 s40, s40, s68
	s_and_b64 vcc, exec, s[38:39]
	s_mov_b64 s[0:1], s[30:31]
	s_mov_b64 s[36:37], s[28:29]
	s_mov_b32 s33, s45
	s_mov_b32 s42, s20
	s_mov_b32 s35, s44
	s_mov_b32 s46, s64
	s_barrier
	s_cbranch_vccnz .LBB0_370

.LBB0_347:
	s_xor_b64 s[38:39], s[38:39], -1
	s_and_b64 vcc, exec, s[38:39]
	s_cbranch_vccnz .Lcvr_LBB0_338
	s_ashr_i32 s22, s20, 6
	s_abs_i32 s21, s22
	v_cvt_f32_u32_e32 v0, s21
	s_sub_i32 s47, 0, s21
	s_abs_i32 s23, s64
	s_xor_b32 s43, s64, s22
	v_rcp_iflag_f32_e32 v0, v0
	s_ashr_i32 s43, s43, 31
	v_mov_b32_e32 v23, v1
	v_mul_f32_e32 v0, 0x4f7ffffe, v0
	v_cvt_u32_f32_e32 v0, v0
	s_nop 0
	v_readfirstlane_b32 s65, v0
	s_mul_i32 s47, s47, s65
	s_mul_hi_u32 s47, s65, s47
	s_add_i32 s65, s65, s47
	s_mul_hi_u32 s47, s23, s65
	s_mul_i32 s65, s47, s21
	s_sub_i32 s23, s23, s65
	s_add_i32 s66, s47, 1
	s_sub_i32 s65, s23, s21
	s_cmp_ge_u32 s23, s21
	s_cselect_b32 s47, s66, s47
	s_cselect_b32 s23, s65, s23
	s_add_i32 s65, s47, 1
	s_cmp_ge_u32 s23, s21
	s_cselect_b32 s23, s65, s47
	s_xor_b32 s23, s23, s43
	s_sub_i32 s23, s23, s43
	s_mul_i32 s22, s23, s22
	v_lshl_add_u32 v0, s23, 6, v21
	s_sub_i32 s43, s64, s22
	v_mad_i64_i32 v[2:3], s[22:23], v0, s20, 0
	s_lshl_b32 s22, s43, 6
	v_lshl_add_u64 v[2:3], v[2:3], 2, s[2:3]
	s_ashr_i32 s23, s22, 31
	s_ashr_i32 s21, s20, 31
	v_lshl_add_u64 v[2:3], s[22:23], 2, v[2:3]
	v_lshl_add_u64 v[2:3], v[2:3], 0, v[22:23]
	s_lshl_b64 s[22:23], s[20:21], 7
	s_waitcnt vmcnt(1)
	v_mov_b64_e32 v[18:19], v[6:7]
	v_mov_b64_e32 v[14:15], v[10:11]
	v_mov_b64_e32 v[16:17], v[4:5]
	v_mov_b64_e32 v[12:13], v[8:9]
	v_lshl_add_u64 v[8:9], v[2:3], 0, s[22:23]
	global_load_dwordx4 v[4:7], v[2:3], off nt
	s_nop 0
	global_load_dwordx4 v[8:11], v[8:9], off nt

.LBB0_386:
	v_ashrrev_i32_e32 v3, 31, v2
	v_lshlrev_b64 v[2:3], 11, v[2:3]
	v_lshl_add_u64 v[2:3], s[0:1], 0, v[2:3]
	s_ashr_i32 s43, s42, 31
	v_lshl_add_u64 v[2:3], s[42:43], 1, v[2:3]
	v_lshlrev_b32_e32 v0, 1, v20
	v_lshl_add_u64 v[2:3], v[2:3], 0, v[0:1]
	global_store_dwordx4 v[2:3], v[12:15], off sc1
	v_readlane_b32 s0, v250, 63
	s_add_i32 s33, s33, s0
	s_and_b64 vcc, exec, s[38:39]
	s_mov_b64 s[0:1], s[36:37]
	s_mov_b64 s[2:3], s[30:31]
	s_mov_b32 s42, s28
	s_mov_b32 s40, s41
	s_mov_b32 s45, s44
	s_barrier
	s_cbranch_vccnz .LBB0_423

.LBB0_400:
	s_xor_b64 s[38:39], s[38:39], -1
	s_and_b64 vcc, exec, s[38:39]
	s_cbranch_vccnz .Lcvr_LBB0_387
	s_ashr_i32 s22, s28, 6
	s_abs_i32 s23, s22
	v_cvt_f32_u32_e32 v0, s23
	s_sub_i32 s46, 0, s23
	s_abs_i32 s29, s44
	s_xor_b32 s43, s44, s22
	v_rcp_iflag_f32_e32 v0, v0
	s_ashr_i32 s43, s43, 31
	v_mov_b32_e32 v23, v1
	v_mul_f32_e32 v0, 0x4f7ffffe, v0
	v_cvt_u32_f32_e32 v0, v0
	s_nop 0
	v_readfirstlane_b32 s47, v0
	s_mul_i32 s46, s46, s47
	s_mul_hi_u32 s46, s47, s46
	s_add_i32 s47, s47, s46
	s_mul_hi_u32 s46, s29, s47
	s_mul_i32 s47, s46, s23
	s_sub_i32 s29, s29, s47
	s_add_i32 s64, s46, 1
	s_sub_i32 s47, s29, s23
	s_cmp_ge_u32 s29, s23
	s_cselect_b32 s46, s64, s46
	s_cselect_b32 s29, s47, s29
	s_add_i32 s47, s46, 1
	s_cmp_ge_u32 s29, s23
	s_cselect_b32 s23, s47, s46
	s_xor_b32 s23, s23, s43
	s_sub_i32 s23, s23, s43
	s_mul_i32 s22, s23, s22
	v_lshl_add_u32 v0, s23, 6, v21
	s_sub_i32 s43, s44, s22
	v_mad_i64_i32 v[2:3], s[22:23], v0, s28, 0
	s_lshl_b32 s22, s43, 6
	v_lshl_add_u64 v[2:3], v[2:3], 2, s[20:21]
	s_ashr_i32 s23, s22, 31
	s_ashr_i32 s29, s28, 31
	v_lshl_add_u64 v[2:3], s[22:23], 2, v[2:3]
	v_lshl_add_u64 v[2:3], v[2:3], 0, v[22:23]
	s_lshl_b64 s[22:23], s[28:29], 7
	s_waitcnt vmcnt(1)
	v_mov_b64_e32 v[18:19], v[6:7]
	v_mov_b64_e32 v[14:15], v[10:11]
	v_mov_b64_e32 v[16:17], v[4:5]
	v_mov_b64_e32 v[12:13], v[8:9]
	v_lshl_add_u64 v[8:9], v[2:3], 0, s[22:23]
	global_load_dwordx4 v[4:7], v[2:3], off nt
	s_nop 0
	global_load_dwordx4 v[8:11], v[8:9], off nt

.LBB0_448:
	s_lshr_b32 s20, s43, 6
	v_cvt_f32_ubyte0_e32 v0, s20
	v_rcp_iflag_f32_e32 v0, v0
	s_sub_i32 s23, 0, s20
	s_abs_i32 s22, s42
	s_ashr_i32 s21, s42, 31
	v_mul_f32_e32 v0, 0x4f7ffffe, v0
	v_cvt_u32_f32_e32 v0, v0
	v_ashrrev_i32_e32 v21, 4, v142
	v_ashrrev_i32_e32 v25, 3, v142
	v_lshl_add_u32 v5, v25, 2, 0
	v_readfirstlane_b32 s28, v0
	s_mul_i32 s23, s23, s28
	s_mul_hi_u32 s23, s28, s23
	s_add_i32 s28, s28, s23
	s_mul_hi_u32 s23, s22, s28
	s_mul_i32 s28, s23, s20
	s_sub_i32 s22, s22, s28
	s_add_i32 s29, s23, 1
	s_sub_i32 s28, s22, s20
	s_cmp_ge_u32 s22, s20
	s_cselect_b32 s23, s29, s23
	s_cselect_b32 s22, s28, s22
	s_add_i32 s28, s23, 1
	s_cmp_ge_u32 s22, s20
	s_cselect_b32 s22, s28, s23
	s_xor_b32 s22, s22, s21
	s_sub_i32 s21, s22, s21
	s_mul_i32 s20, s21, s20
	v_lshl_add_u32 v0, s21, 6, v21
	s_sub_i32 s22, s42, s20
	v_mad_i64_i32 v[2:3], s[20:21], v0, s43, 0
	v_lshl_add_u64 v[2:3], v[2:3], 2, s[2:3]
	s_lshl_b32 s2, s22, 6
	v_lshlrev_b32_e32 v0, 2, v142
	s_ashr_i32 s3, s2, 31
	v_and_b32_e32 v4, 60, v0
	v_lshl_add_u64 v[2:3], s[2:3], 2, v[2:3]
	v_lshlrev_b32_e32 v0, 2, v4
	v_lshl_add_u64 v[2:3], v[2:3], 0, v[0:1]
	s_lshl_b32 s96, s43, 7
	v_lshl_add_u64 v[6:7], v[2:3], 0, s[96:97]
	global_load_dwordx4 v[16:19], v[2:3], off nt
	global_load_dwordx4 v[12:15], v[6:7], off nt
	s_movk_i32 s2, 0x104
	v_mul_lo_u32 v2, v21, s2
	v_add3_u32 v24, 0, v2, v0
	v_lshlrev_b32_e32 v0, 3, v142
	v_and_b32_e32 v20, 56, v0
	v_mul_u32_u24_e32 v6, 0x104, v20
	v_mov_b32_e32 v2, v1
	v_mov_b32_e32 v3, v1
	v_mov_b32_e32 v0, v1
	v_lshlrev_b32_e32 v22, 2, v4
	v_add_u32_e32 v26, v5, v6
	v_mov_b64_e32 v[6:7], v[2:3]
	v_mov_b64_e32 v[10:11], v[2:3]
	v_readlane_b32 s35, v250, 15
	v_mov_b64_e32 v[4:5], v[0:1]
	v_mov_b64_e32 v[8:9], v[0:1]
	s_waitcnt vmcnt(0)
	v_mov_b64_e32 v[6:7], v[18:19]
	v_mov_b64_e32 v[10:11], v[14:15]
	v_mov_b64_e32 v[4:5], v[16:17]
	v_mov_b64_e32 v[8:9], v[12:13]
	s_branch .LBB0_453

.LBB0_452:
	v_mad_i64_i32 v[2:3], s[22:23], v2, s33, 0
	v_lshl_add_u64 v[2:3], v[2:3], 1, s[0:1]
	s_ashr_i32 s39, s38, 31
	v_lshl_add_u64 v[2:3], s[38:39], 1, v[2:3]
	v_lshlrev_b32_e32 v0, 1, v20
	v_lshl_add_u64 v[2:3], v[2:3], 0, v[0:1]
	global_store_dwordx4 v[2:3], v[12:15], off sc1
	s_cmpk_lt_i32 s35, 0x840
	s_mov_b64 s[0:1], s[30:31]
	s_mov_b64 s[36:37], s[20:21]
	s_mov_b32 s33, s45
	s_mov_b32 s43, s28
	s_mov_b32 s40, s44
	s_mov_b32 s42, s41
	s_barrier
	s_cbranch_scc0 .LBB0_484

.LBB0_460:
	s_ashr_i32 s22, s28, 6
	s_abs_i32 s23, s22
	v_cvt_f32_u32_e32 v0, s23
	s_sub_i32 s39, 0, s23
	s_abs_i32 s29, s41
	s_xor_b32 s38, s41, s22
	v_rcp_iflag_f32_e32 v0, v0
	s_ashr_i32 s38, s38, 31
	v_mov_b32_e32 v23, v1
	v_mul_f32_e32 v0, 0x4f7ffffe, v0
	v_cvt_u32_f32_e32 v0, v0
	s_nop 0
	v_readfirstlane_b32 s46, v0
	s_mul_i32 s39, s39, s46
	s_mul_hi_u32 s39, s46, s39
	s_add_i32 s46, s46, s39
	s_mul_hi_u32 s39, s29, s46
	s_mul_i32 s46, s39, s23
	s_sub_i32 s29, s29, s46
	s_add_i32 s47, s39, 1
	s_sub_i32 s46, s29, s23
	s_cmp_ge_u32 s29, s23
	s_cselect_b32 s39, s47, s39
	s_cselect_b32 s29, s46, s29
	s_add_i32 s46, s39, 1
	s_cmp_ge_u32 s29, s23
	s_cselect_b32 s23, s46, s39
	s_xor_b32 s23, s23, s38
	s_sub_i32 s23, s23, s38
	s_mul_i32 s22, s23, s22
	v_lshl_add_u32 v0, s23, 6, v21
	s_sub_i32 s38, s41, s22
	v_mad_i64_i32 v[2:3], s[22:23], v0, s28, 0
	s_lshl_b32 s22, s38, 6
	v_lshl_add_u64 v[2:3], v[2:3], 2, s[2:3]
	s_ashr_i32 s23, s22, 31
	s_ashr_i32 s29, s28, 31
	v_lshl_add_u64 v[2:3], s[22:23], 2, v[2:3]
	v_lshl_add_u64 v[2:3], v[2:3], 0, v[22:23]
	s_lshl_b64 s[22:23], s[28:29], 7
	s_waitcnt vmcnt(1)
	v_mov_b64_e32 v[18:19], v[6:7]
	v_mov_b64_e32 v[14:15], v[10:11]
	v_mov_b64_e32 v[16:17], v[4:5]
	v_mov_b64_e32 v[12:13], v[8:9]
	v_lshl_add_u64 v[8:9], v[2:3], 0, s[22:23]
	global_load_dwordx4 v[4:7], v[2:3], off nt
	s_nop 0
	global_load_dwordx4 v[8:11], v[8:9], off nt

.LBB0_484:
	v_readlane_b32 s0, v250, 23
	v_readlane_b32 s1, v250, 24
	v_readlane_b32 s44, v255, 0
	s_andn2_b64 vcc, exec, s[0:1]
	v_readlane_b32 s40, v254, 63
	s_mov_b32 s41, s25
	v_readlane_b32 s25, v250, 22
	v_readlane_b32 s45, v255, 1
	s_cbranch_vccnz .LBB0_503
	v_ashrrev_i32_e32 v21, 4, v142
	v_readlane_b32 s0, v250, 26
	v_ashrrev_i32_e32 v25, 3, v142
	v_lshl_add_u32 v5, v25, 2, 0
	v_add_u32_e32 v0, s0, v21
	v_readlane_b32 s0, v250, 27
	v_readlane_b32 s1, v250, 28
	v_readlane_b32 s2, v250, 25
	s_mov_b32 s28, s2
	v_mov_b64_e32 v[2:3], s[0:1]
	s_movk_i32 s0, 0x7000
	v_mad_i64_i32 v[2:3], s[0:1], v0, s0, v[2:3]
	v_lshlrev_b32_e32 v0, 2, v142
	v_and_b32_e32 v4, 60, v0
	v_lshlrev_b32_e32 v0, 2, v4
	v_lshl_add_u64 v[2:3], v[2:3], 0, v[0:1]
	v_add_co_u32_e32 v6, vcc, 0xe0000, v2
	s_movk_i32 s0, 0x104
	s_nop 0
	v_addc_co_u32_e32 v7, vcc, 0, v3, vcc
	global_load_dwordx4 v[12:15], v[2:3], off nt
	global_load_dwordx4 v[16:19], v[6:7], off nt
	v_mul_lo_u32 v2, v21, s0
	v_add3_u32 v24, 0, v2, v0
	v_lshlrev_b32_e32 v0, 3, v142
	v_and_b32_e32 v20, 56, v0
	v_mul_u32_u24_e32 v6, 0x104, v20
	v_mov_b32_e32 v2, v1
	v_mov_b32_e32 v3, v1
	v_mov_b32_e32 v0, v1
	v_lshlrev_b32_e32 v22, 2, v4
	v_add_u32_e32 v26, v5, v6
	v_mov_b64_e32 v[6:7], v[2:3]
	v_mov_b64_e32 v[10:11], v[2:3]
	v_mov_b64_e32 v[4:5], v[0:1]
	v_mov_b64_e32 v[8:9], v[0:1]
	s_waitcnt vmcnt(0)
	v_mov_b64_e32 v[10:11], v[18:19]
	v_mov_b64_e32 v[6:7], v[14:15]
	v_mov_b64_e32 v[4:5], v[12:13]
	v_mov_b64_e32 v[8:9], v[16:17]
	s_branch .LBB0_489
.Lcvr_LBB0_489:
	s_waitcnt vmcnt(1)
	v_mov_b64_e32 v[18:19], v[10:11]
	v_mov_b64_e32 v[14:15], v[6:7]
	v_mov_b64_e32 v[12:13], v[4:5]
	v_mov_b64_e32 v[16:17], v[8:9]
	s_branch .LBB0_493

.LBB0_488:
	s_or_b64 exec, exec, s[2:3]
	v_ashrrev_i32_e32 v3, 31, v2
	v_lshlrev_b64 v[2:3], 11, v[2:3]
	v_lshl_add_u64 v[2:3], s[44:45], 0, v[2:3]
	s_ashr_i32 s1, s0, 31
	v_lshl_add_u64 v[2:3], s[0:1], 1, v[2:3]
	v_lshlrev_b32_e32 v0, 1, v20
	v_lshl_add_u64 v[2:3], v[2:3], 0, v[0:1]
	global_store_dwordx4 v[2:3], v[12:15], off sc1
	s_add_i32 s28, s28, s25
	s_cmpk_gt_i32 s28, 0x43f
	s_mov_b32 s2, s29
	s_barrier
	s_cbranch_scc1 .LBB0_503

.LBB0_491:
	s_andn2_b64 vcc, exec, s[0:1]
	s_cbranch_vccnz .Lcvr_LBB0_489
	s_mul_hi_i32 s0, s29, 0x92492493
	s_add_i32 s0, s0, s29
	s_lshr_b32 s1, s0, 31
	s_ashr_i32 s0, s0, 6
	v_readlane_b32 s64, v251, 55
	s_add_i32 s0, s0, s1
	v_readlane_b32 s74, v252, 1
	v_readlane_b32 s75, v252, 2
	s_mul_i32 s1, s0, 0xffffff90
	v_lshl_add_u32 v0, s0, 6, v21
	v_mov_b64_e32 v[2:3], s[74:75]
	s_movk_i32 s0, 0x7000
	s_add_i32 s3, s1, s29
	v_mad_i64_i32 v[2:3], s[0:1], v0, s0, v[2:3]
	s_lshl_b32 s0, s3, 6
	s_ashr_i32 s1, s0, 31
	v_lshl_add_u64 v[2:3], s[0:1], 2, v[2:3]
	v_mov_b32_e32 v23, v1
	v_lshl_add_u64 v[2:3], v[2:3], 0, v[22:23]
	s_waitcnt vmcnt(1)
	v_mov_b64_e32 v[18:19], v[10:11]
	v_mov_b64_e32 v[14:15], v[6:7]
	v_mov_b64_e32 v[12:13], v[4:5]
	v_mov_b64_e32 v[16:17], v[8:9]
	v_add_co_u32_e32 v8, vcc, 0xe0000, v2
	v_readlane_b32 s65, v251, 56
	s_nop 0
	v_addc_co_u32_e32 v9, vcc, 0, v3, vcc
	global_load_dwordx4 v[4:7], v[2:3], off nt
	s_nop 0
	global_load_dwordx4 v[8:11], v[8:9], off nt
	v_readlane_b32 s66, v251, 57
	v_readlane_b32 s67, v251, 58
	v_readlane_b32 s68, v251, 59
	v_readlane_b32 s69, v251, 60
	v_readlane_b32 s70, v251, 61
	v_readlane_b32 s71, v251, 62
	v_readlane_b32 s72, v251, 63
	v_readlane_b32 s73, v252, 0
	v_readlane_b32 s76, v252, 3
	v_readlane_b32 s77, v252, 4
	v_readlane_b32 s78, v252, 5
	v_readlane_b32 s79, v252, 6
